# v16 = v13 + P2 within-row shuffles (pre-pass sums, kv epilogue key-norm maxima) as DPP moves instead of ds_bpermute
# baseline (speedup 1.0000x reference)
.LBB0_393:
	s_or_b64 exec, exec, s[2:3]
	s_add_u32 s2, s4, 0xc00000
	s_addc_u32 s3, s5, 0
	s_add_u32 s0, s4, 0xfb00000
	s_addc_u32 s1, s5, 0
	s_cmp_gt_u32 s31, 1
	s_cselect_b64 s[10:11], -1, 0
	s_cmp_lt_u32 s31, 5
	s_cselect_b32 s7, -1, -4
	s_add_i32 s7, s7, s31
	s_cmp_lt_u32 s31, 2
	s_cselect_b64 s[8:9], -1, 0
	s_and_b64 s[12:13], s[8:9], exec
	s_cselect_b32 s18, 0, s7
	s_ashr_i32 s7, s6, 31
	s_lshl_b64 s[12:13], s[6:7], 8
	s_lshl_b32 s7, s18, 6
	s_ashr_i32 s14, s7, 31
	v_and_b32_e32 v3, 15, v0
	s_add_u32 s12, s12, s7
	v_ashrrev_i32_e32 v0, 4, v2
	s_addc_u32 s13, s13, s14
	v_ashrrev_i32_e32 v1, 31, v0
	v_lshl_add_u64 v[4:5], s[12:13], 0, v[0:1]
	v_lshlrev_b64 v[6:7], 5, v[4:5]
	v_or_b32_e32 v6, v6, v3
	v_or_b32_e32 v8, 16, v6
	v_mov_b32_e32 v9, v7
	v_lshl_add_u64 v[10:11], v[8:9], 2, s[2:3]
	v_lshl_add_u64 v[0:1], v[6:7], 2, s[2:3]
	global_load_dword v12, v[10:11], off
	global_load_dword v13, v[0:1], off
	v_mov_b32_e32 v1, 0
	v_lshlrev_b32_e32 v0, 3, v3
	v_lshl_add_u64 v[0:1], s[4:5], 0, v[0:1]
	s_mov_b64 s[14:15], 0x100000
	v_lshl_add_u64 v[0:1], v[0:1], 0, s[14:15]
	v_lshlrev_b64 v[4:5], 7, v[4:5]
	v_lshl_add_u64 v[4:5], v[0:1], 0, v[4:5]
	global_load_dwordx2 v[10:11], v[4:5], off
	v_mbcnt_lo_u32_b32 v4, -1, 0
	v_mbcnt_hi_u32_b32 v4, -1, v4
	v_and_b32_e32 v14, 64, v4
	v_xor_b32_e32 v5, 1, v4
	v_add_u32_e32 v14, 64, v14
	v_cmp_lt_i32_e32 vcc, v5, v14
	v_xor_b32_e32 v17, 32, v4
	s_movk_i32 s14, 0x7fff
	v_cndmask_b32_e32 v5, v4, v5, vcc
	v_lshlrev_b32_e32 v146, 2, v5
	v_xor_b32_e32 v5, 2, v4
	v_cmp_lt_i32_e32 vcc, v5, v14
	v_lshl_add_u64 v[6:7], v[6:7], 1, s[0:1]
	v_lshl_add_u64 v[8:9], v[8:9], 1, s[0:1]
	v_cndmask_b32_e32 v5, v4, v5, vcc
	v_lshlrev_b32_e32 v147, 2, v5
	v_xor_b32_e32 v5, 4, v4
	v_cmp_lt_i32_e32 vcc, v5, v14
	s_mov_b32 s7, 0
	s_waitcnt vmcnt(2)
	v_mul_f32_e32 v15, v12, v12
	s_waitcnt vmcnt(1)
	v_fmac_f32_e32 v15, v13, v13
	s_nop 1
	v_mov_b32_dpp v16, v15 quad_perm:[1,0,3,2] row_mask:0xf bank_mask:0xf
	v_cndmask_b32_e32 v5, v4, v5, vcc
	v_lshlrev_b32_e32 v148, 2, v5
	v_xor_b32_e32 v5, 8, v4
	v_cmp_lt_i32_e32 vcc, v5, v14
	s_waitcnt lgkmcnt(0)
	v_add_f32_e32 v15, v15, v16
	s_nop 1
	v_mov_b32_dpp v16, v15 quad_perm:[2,3,0,1] row_mask:0xf bank_mask:0xf
	v_cndmask_b32_e32 v5, v4, v5, vcc
	v_lshlrev_b32_e32 v149, 2, v5
	v_xor_b32_e32 v5, 16, v4
	v_cmp_lt_i32_e32 vcc, v5, v14
	s_nop 1
	v_cndmask_b32_e32 v5, v4, v5, vcc
	v_cmp_lt_i32_e32 vcc, v17, v14
	s_waitcnt lgkmcnt(0)
	v_add_f32_e32 v14, v15, v16
	s_nop 1
	v_mov_b32_dpp v15, v14 row_half_mirror row_mask:0xf bank_mask:0xf
	s_waitcnt vmcnt(0)
	v_mul_f32_e32 v16, v12, v11
	v_fma_f32 v16, v13, v10, -v16
	v_cndmask_b32_e32 v4, v4, v17, vcc
	v_bfe_u32 v17, v16, 16, 1
	s_waitcnt lgkmcnt(0)
	v_add_f32_e32 v14, v14, v15
	s_nop 1
	v_mov_b32_dpp v15, v14 row_mirror row_mask:0xf bank_mask:0xf
	v_add3_u32 v16, v16, v17, s14
	v_lshlrev_b32_e32 v5, 2, v5
	global_store_short_d16_hi v[6:7], v16, off
	v_lshlrev_b32_e32 v4, 2, v4
	s_waitcnt lgkmcnt(0)
	v_add_f32_e32 v6, v14, v15
	ds_bpermute_b32 v7, v5, v6
	v_mul_f32_e32 v11, v13, v11
	v_fmac_f32_e32 v11, v12, v10
	v_bfe_u32 v10, v11, 16, 1
	v_add3_u32 v10, v11, v10, s14
	s_waitcnt lgkmcnt(0)
	v_max_f32_e32 v7, v7, v7
	v_max_f32_e32 v6, v6, v7
	ds_bpermute_b32 v7, v4, v6
	global_store_short_d16_hi v[8:9], v10, off
	v_mbcnt_lo_u32_b32 v8, -1, 0
	v_mbcnt_hi_u32_b32 v8, -1, v8
	s_nop 0
	v_cmp_eq_u32_e32 vcc, 0, v8
	s_and_saveexec_b64 s[14:15], vcc
	s_cbranch_execz .LBB0_398
	s_waitcnt lgkmcnt(0)
	v_max_f32_e32 v7, v7, v7
	v_max_f32_e32 v6, v6, v6
	s_mov_b64 s[16:17], exec
	v_max_f32_e32 v6, v6, v7

.LBB0_398:
	s_or_b64 exec, exec, s[14:15]
	v_add_u32_e32 v6, 0x200, v2
	v_ashrrev_i32_e32 v6, 4, v6
	s_waitcnt lgkmcnt(0)
	v_ashrrev_i32_e32 v7, 31, v6
	v_lshl_add_u64 v[6:7], s[12:13], 0, v[6:7]
	v_lshlrev_b64 v[8:9], 5, v[6:7]
	v_or_b32_e32 v8, v8, v3
	v_or_b32_e32 v12, 16, v8
	v_mov_b32_e32 v13, v9
	v_lshl_add_u64 v[14:15], v[12:13], 2, s[2:3]
	v_lshl_add_u64 v[10:11], v[8:9], 2, s[2:3]
	global_load_dword v3, v[14:15], off
	global_load_dword v16, v[10:11], off
	v_lshlrev_b64 v[6:7], 7, v[6:7]
	v_lshl_add_u64 v[0:1], v[0:1], 0, v[6:7]
	global_load_dwordx2 v[0:1], v[0:1], off
	s_movk_i32 s2, 0x7fff
	s_mov_b32 s7, 0
	s_waitcnt vmcnt(2)
	v_mul_f32_e32 v6, v3, v3
	s_waitcnt vmcnt(1)
	v_fmac_f32_e32 v6, v16, v16
	s_nop 1
	v_mov_b32_dpp v7, v6 quad_perm:[1,0,3,2] row_mask:0xf bank_mask:0xf
	s_waitcnt vmcnt(0)
	v_mul_f32_e32 v10, v3, v1
	v_mul_f32_e32 v1, v16, v1
	v_fmac_f32_e32 v1, v3, v0
	s_waitcnt lgkmcnt(0)
	v_add_f32_e32 v6, v6, v7
	s_nop 1
	v_mov_b32_dpp v7, v6 quad_perm:[2,3,0,1] row_mask:0xf bank_mask:0xf
	v_fma_f32 v10, v16, v0, -v10
	v_bfe_u32 v0, v1, 16, 1
	v_add3_u32 v3, v1, v0, s2
	v_bfe_u32 v11, v10, 16, 1
	s_waitcnt lgkmcnt(0)
	v_add_f32_e32 v6, v6, v7
	s_nop 1
	v_mov_b32_dpp v7, v6 row_half_mirror row_mask:0xf bank_mask:0xf
	v_add3_u32 v10, v10, v11, s2
	s_waitcnt lgkmcnt(0)
	v_add_f32_e32 v14, v6, v7
	s_nop 1
	v_mov_b32_dpp v15, v14 row_mirror row_mask:0xf bank_mask:0xf
	v_lshl_add_u64 v[6:7], v[8:9], 1, s[0:1]
	global_store_short_d16_hi v[6:7], v10, off
	v_lshl_add_u64 v[6:7], v[12:13], 1, s[0:1]
	global_store_short_d16_hi v[6:7], v3, off
	s_waitcnt lgkmcnt(0)
	v_add_f32_e32 v8, v14, v15
	ds_bpermute_b32 v5, v5, v8
	v_mbcnt_lo_u32_b32 v3, -1, 0
	v_mbcnt_hi_u32_b32 v3, -1, v3
	s_waitcnt lgkmcnt(0)
	v_max_f32_e32 v0, v5, v5
	v_max_f32_e32 v0, v8, v0
	ds_bpermute_b32 v1, v4, v0
	v_cmp_eq_u32_e32 vcc, 0, v3
	s_and_saveexec_b64 s[0:1], vcc
	s_cbranch_execz .LBB0_403
	s_waitcnt lgkmcnt(0)
	v_max_f32_e32 v1, v1, v1
	v_max_f32_e32 v0, v0, v0
	s_mov_b64 s[2:3], exec
	v_max_f32_e32 v0, v0, v1

.LBB0_457:
	v_mov_b32_e32 v135, v134
	v_mov_b32_e32 v136, v134
	v_mov_b32_e32 v137, v134
	v_pk_mul_f32 v[138:139], v[50:51], v[136:137]
	v_pk_mul_f32 v[140:141], v[48:49], v[134:135]
	v_pk_mul_f32 v[136:137], v[42:43], v[136:137]
	v_pk_mul_f32 v[134:135], v[40:41], v[134:135]
	v_lshl_add_u64 v[132:133], s[14:15], 1, v[132:133]
	s_and_b64 vcc, exec, s[2:3]
	v_cvt_pk_bf16_f32 v142, v140, v141
	v_cvt_pk_bf16_f32 v143, v138, v139
	v_cvt_pk_bf16_f32 v144, v134, v135
	v_cvt_pk_bf16_f32 v145, v136, v137
	global_store_dwordx4 v[132:133], v[142:145], off sc1
	s_cbranch_vccnz .LBB0_463
	v_mul_f32_e32 v129, v141, v141
	v_mul_f32_e32 v132, v139, v139
	v_fmac_f32_e32 v129, v140, v140
	v_fmac_f32_e32 v132, v138, v138
	v_add_f32_e32 v129, v129, v132
	v_mul_f32_e32 v132, v135, v135
	v_fmac_f32_e32 v132, v134, v134
	s_nop 1
	v_mov_b32_dpp v134, v130 quad_perm:[1,0,3,2] row_mask:0xf bank_mask:0xf
	v_mul_f32_e32 v133, v137, v137
	v_fmac_f32_e32 v133, v136, v136
	v_add_f32_e32 v132, v132, v133
	v_max_f32_e32 v130, v130, v130
	s_waitcnt lgkmcnt(0)
	v_max_f32_e32 v133, v134, v134
	v_max_f32_e32 v133, v130, v133
	s_nop 1
	v_mov_b32_dpp v134, v133 quad_perm:[2,3,0,1] row_mask:0xf bank_mask:0xf
	v_add_f32_e32 v129, v129, v132
	v_mov_b32_e32 v132, v129
	s_nop 1
	v_permlane16_swap_b32_e32 v129, v132
	v_add_f32_e32 v129, v129, v132
	s_waitcnt lgkmcnt(0)
	v_max_f32_e32 v132, v134, v134
	v_max_f32_e32 v132, v133, v132
	s_nop 1
	v_mov_b32_dpp v133, v132 row_half_mirror row_mask:0xf bank_mask:0xf
	s_lshr_b32 s2, s73, 5
	s_mul_i32 s14, s2, 12
	s_lshl_b32 s2, s73, 1
	v_mov_b32_e32 v130, v129
	s_waitcnt lgkmcnt(0)
	v_max_f32_e32 v133, v133, v133
	v_max_f32_e32 v132, v132, v133
	s_nop 1
	v_mov_b32_dpp v133, v132 row_mirror row_mask:0xf bank_mask:0xf
	s_and_b32 s2, s2, 62
	v_permlane32_swap_b32_e32 v129, v130
	v_cmp_eq_u32_e32 vcc, 0, v159
	s_add_i32 s14, s14, s74
	s_add_i32 s26, s59, s2
	s_and_saveexec_b64 s[2:3], vcc
	s_cbranch_execz .LBB0_460
	s_lshl_b32 s27, s14, 7
	s_add_i32 s74, s27, s26
	s_ashr_i32 s75, s74, 31
	s_lshl_b64 s[74:75], s[74:75], 2
	s_add_u32 s74, s47, s74
	s_waitcnt lgkmcnt(0)
	v_max_f32_e32 v133, v133, v133
	v_max_f32_e32 v132, v132, v132
	s_addc_u32 s75, s48, s75
	v_max_f32_e32 v132, v132, v133
	global_store_dword v128, v132, s[74:75]
.LBB0_460:
	s_or_b64 exec, exec, s[2:3]
	v_add_f32_e32 v129, v129, v130
	v_max_f32_e32 v130, v131, v131
	v_max_f32_e32 v129, v130, v129
	s_nop 1
	v_mov_b32_dpp v130, v129 quad_perm:[1,0,3,2] row_mask:0xf bank_mask:0xf
	s_waitcnt lgkmcnt(0)
	v_max_f32_e32 v130, v130, v130
	v_max_f32_e32 v129, v129, v130
	s_nop 1
	v_mov_b32_dpp v130, v129 quad_perm:[2,3,0,1] row_mask:0xf bank_mask:0xf
	s_waitcnt lgkmcnt(0)
	v_max_f32_e32 v130, v130, v130
	v_max_f32_e32 v129, v129, v130
	s_nop 1
	v_mov_b32_dpp v130, v129 row_half_mirror row_mask:0xf bank_mask:0xf
	s_waitcnt lgkmcnt(0)
	v_max_f32_e32 v130, v130, v130
	v_max_f32_e32 v129, v129, v130
	s_nop 1
	v_mov_b32_dpp v130, v129 row_mirror row_mask:0xf bank_mask:0xf
	s_and_saveexec_b64 s[2:3], vcc
	s_cbranch_execz .LBB0_462
	s_lshl_b32 s14, s14, 7
	s_add_i32 s14, s26, s14
	s_add_i32 s26, s14, 0x80
	s_ashr_i32 s27, s26, 31
	s_lshl_b64 s[26:27], s[26:27], 2
	s_waitcnt lgkmcnt(0)
	v_max_f32_e32 v130, v130, v130
	v_max_f32_e32 v129, v129, v129
	s_add_u32 s26, s47, s26
	v_max_f32_e32 v129, v129, v130
	s_addc_u32 s27, s48, s27
	global_store_dword v128, v129, s[26:27]
